# NSA QK fragment reads hoisted, top-k LDS prefetch, RWKV wave priority 3->1
# speedup vs baseline: 1.0525x; 1.0019x over previous
.LBB0_184:
	s_waitcnt vmcnt(63) expcnt(7) lgkmcnt(15)
	s_barrier
	global_load_dwordx4 v[2:5], v[20:21], off
	v_subrev_u32_e32 v28, 48, v0
	v_subrev_u32_e32 v29, 32, v0
	v_add_u32_e32 v30, -16, v0
	v_add_u32_e32 v7, 0xfffffe50, v0
	v_add_u32_e32 v8, 0xfffffe60, v0
	v_add_u32_e32 v9, 0xfffffe70, v0
	v_add_u32_e32 v10, 0xfffffe80, v0
	v_add_u32_e32 v11, 0xfffffed0, v0
	v_add_u32_e32 v12, 0xfffffee0, v0
	v_add_u32_e32 v13, 0xfffffef0, v0
	v_add_u32_e32 v14, 0xffffff00, v0
	v_add_u32_e32 v15, 0xffffff50, v0
	v_add_u32_e32 v16, 0xffffff60, v0
	v_add_u32_e32 v17, 0xffffff70, v0
	v_cmp_gt_i32_e64 s[62:63], v28, v50
	v_cmp_gt_i32_e64 s[64:65], v29, v50
	v_cmp_gt_i32_e64 s[66:67], v30, v50
	v_mov_b32_e32 v32, v6
	v_cmp_gt_i32_e64 s[38:39], v7, v50
	v_cmp_gt_i32_e64 s[40:41], v8, v50
	v_cmp_gt_i32_e64 s[42:43], v9, v50
	v_cmp_gt_i32_e64 s[44:45], v10, v50
	v_cmp_gt_i32_e64 s[46:47], v11, v50
	v_cmp_gt_i32_e64 s[48:49], v12, v50
	v_cmp_gt_i32_e64 s[50:51], v13, v50
	v_cmp_gt_i32_e64 s[52:53], v14, v50
	v_cmp_gt_i32_e64 s[54:55], v15, v50
	v_cmp_gt_i32_e64 s[56:57], v16, v50
	v_cmp_gt_i32_e64 s[58:59], v17, v50
	v_mov_b32_e32 v27, v19
	v_add_u32_e32 v19, 0xffffff80, v0
	v_cmp_gt_i32_e64 s[60:61], v19, v50
	v_cmp_gt_i32_e32 vcc, v0, v50
	s_add_i32 s6, s6, -1
	v_lshl_add_u64 v[20:21], v[20:21], 0, s[94:95]
	v_add_u32_e32 v0, 0x200, v0
	s_cmp_eq_u32 s6, 0
	s_waitcnt vmcnt(0)
	ds_write_b128 v18, v[2:5]
	s_waitcnt lgkmcnt(0)
	s_barrier
	ds_read_b128 v[2:5], v63
	ds_read_b128 v[28:31], v63 offset:32
	ds_read_b128 v[220:223], v63 offset:64
	ds_read_b128 v[224:227], v63 offset:96
	s_waitcnt lgkmcnt(3)
	v_mfma_f32_32x32x16_bf16 v[2:17], v[2:5], v[96:99], 0
	s_waitcnt lgkmcnt(2)
	v_mfma_f32_32x32x16_bf16 v[2:17], v[28:31], v[100:103], v[2:17]
	s_waitcnt lgkmcnt(1)
	v_mfma_f32_32x32x16_bf16 v[2:17], v[220:223], v[104:107], v[2:17]
	s_waitcnt lgkmcnt(0)
	v_mfma_f32_32x32x16_bf16 v[2:17], v[224:227], v[108:111], v[2:17]
	s_nop 11
	v_max_f32_e32 v19, v2, v2
	v_max_f32_e32 v19, 0xf149f2ca, v19
	v_cndmask_b32_e64 v28, v3, v202, s[40:41]
	v_cndmask_b32_e64 v29, v4, v202, s[42:43]
	v_cndmask_b32_e64 v19, v19, v202, s[38:39]
	v_cndmask_b32_e64 v30, v5, v202, s[44:45]
	v_cndmask_b32_e64 v31, v6, v202, s[46:47]
	v_max3_f32 v19, v19, v28, v29
	v_cndmask_b32_e64 v33, v7, v202, s[48:49]
	v_cndmask_b32_e64 v34, v8, v202, s[50:51]
	v_max3_f32 v19, v19, v30, v31
	v_cndmask_b32_e64 v35, v9, v202, s[52:53]
	v_cndmask_b32_e64 v36, v10, v202, s[54:55]
	v_max3_f32 v19, v19, v33, v34
	v_cndmask_b32_e64 v37, v11, v202, s[56:57]
	v_cndmask_b32_e64 v38, v12, v202, s[58:59]
	v_max3_f32 v19, v19, v35, v36
	v_cndmask_b32_e64 v39, v13, v202, s[60:61]
	v_cndmask_b32_e64 v40, v14, v202, s[62:63]
	v_max3_f32 v19, v19, v37, v38
	v_cndmask_b32_e64 v41, v15, v202, s[64:65]
	v_cndmask_b32_e64 v42, v16, v202, s[66:67]
	v_max3_f32 v19, v19, v39, v40
	v_cndmask_b32_e32 v43, v17, v202, vcc
	v_max3_f32 v19, v19, v41, v42
	v_max3_f32 v19, v27, v19, v43
	v_sub_f32_e32 v2, v2, v19
	v_sub_f32_e32 v3, v3, v19
	v_exp_f32_e32 v2, v2
	v_sub_f32_e32 v4, v4, v19
	v_exp_f32_e32 v3, v3
	v_sub_f32_e32 v5, v5, v19
	v_exp_f32_e32 v4, v4
	v_sub_f32_e32 v6, v6, v19
	v_exp_f32_e32 v5, v5
	v_sub_f32_e32 v7, v7, v19
	v_exp_f32_e32 v6, v6
	v_add_f32_e32 v2, 0, v2
	v_sub_f32_e32 v8, v8, v19
	v_exp_f32_e32 v7, v7
	v_cndmask_b32_e64 v3, v3, 0, s[40:41]
	v_cndmask_b32_e64 v2, v2, 0, s[38:39]
	v_sub_f32_e32 v9, v9, v19
	v_exp_f32_e32 v8, v8
	v_cndmask_b32_e64 v4, v4, 0, s[42:43]
	v_add_f32_e32 v2, v3, v2
	v_sub_f32_e32 v10, v10, v19
	v_exp_f32_e32 v9, v9
	v_cndmask_b32_e64 v5, v5, 0, s[44:45]
	v_add_f32_e32 v2, v4, v2
	v_sub_f32_e32 v11, v11, v19
	v_exp_f32_e32 v10, v10
	v_cndmask_b32_e64 v6, v6, 0, s[46:47]
	v_add_f32_e32 v2, v5, v2
	v_sub_f32_e32 v12, v12, v19
	v_exp_f32_e32 v11, v11
	v_cndmask_b32_e64 v7, v7, 0, s[48:49]
	v_add_f32_e32 v2, v6, v2
	v_sub_f32_e32 v13, v13, v19
	v_exp_f32_e32 v12, v12
	v_cndmask_b32_e64 v8, v8, 0, s[50:51]
	v_add_f32_e32 v2, v7, v2
	v_sub_f32_e32 v14, v14, v19
	v_exp_f32_e32 v13, v13
	v_cndmask_b32_e64 v9, v9, 0, s[52:53]
	v_add_f32_e32 v2, v8, v2
	v_sub_f32_e32 v15, v15, v19
	v_exp_f32_e32 v14, v14
	v_cndmask_b32_e64 v10, v10, 0, s[54:55]
	v_add_f32_e32 v2, v9, v2
	v_sub_f32_e32 v16, v16, v19
	v_exp_f32_e32 v15, v15
	v_cndmask_b32_e64 v11, v11, 0, s[56:57]
	v_add_f32_e32 v2, v10, v2
	v_sub_f32_e32 v17, v17, v19
	v_exp_f32_e32 v16, v16
	v_cndmask_b32_e64 v12, v12, 0, s[58:59]
	v_add_f32_e32 v2, v11, v2
	v_exp_f32_e32 v17, v17
	v_cndmask_b32_e64 v13, v13, 0, s[60:61]
	v_add_f32_e32 v2, v12, v2
	v_sub_f32_e32 v27, v27, v19
	v_cndmask_b32_e64 v14, v14, 0, s[62:63]
	v_add_f32_e32 v2, v13, v2
	v_exp_f32_e32 v27, v27
	v_cndmask_b32_e64 v15, v15, 0, s[64:65]
	v_add_f32_e32 v2, v14, v2
	v_cndmask_b32_e64 v16, v16, 0, s[66:67]
	v_add_f32_e32 v2, v15, v2
	v_cndmask_b32_e64 v17, v17, 0, vcc
	v_add_f32_e32 v2, v16, v2
	v_add_f32_e32 v6, v17, v2
	v_fmac_f32_e32 v6, v32, v27
	s_cbranch_scc0 .LBB0_184
	v_readlane_b32 s64, v253, 17
	v_readlane_b32 s65, v253, 18
	s_mov_b64 s[66:67], s[14:15]
	s_branch .LBB0_187

.LBB0_209:
	s_or_b64 exec, exec, s[4:5]
	s_cmp_lt_i32 s10, 16
	ds_write_b32 v47, v41 offset:28
	s_cselect_b64 s[62:63], -1, 0
	v_lshl_add_u32 v45, v35, 2, v203
	v_mov_b32_e32 v41, 0
	v_mov_b32_e32 v43, 0
	s_waitcnt lgkmcnt(0)
	s_barrier
	s_and_saveexec_b64 s[4:5], s[50:51]
	s_cbranch_execz .LBB0_218
	v_cmp_eq_u32_e64 s[50:51], 0, v0
	v_cmp_eq_u32_e64 s[52:53], s10, v0
	s_or_b64 s[6:7], s[52:53], s[50:51]
	s_nor_b64 s[14:15], s[62:63], s[6:7]
	v_mov_b32_e32 v43, 1
	s_and_saveexec_b64 s[6:7], s[14:15]
	s_cbranch_execz .LBB0_217
	v_lshl_add_u32 v35, v0, 2, v45
	ds_read_b32 v46, v35
	s_add_i32 s13, s10, -1
	s_and_b32 s15, s13, -2
	s_mov_b32 s14, 2
	v_mov_b32_e32 v35, v0
	s_waitcnt lgkmcnt(0)
	v_mov_b32_e32 v37, v46
	v_add_u32_e32 v48, 0x11204, v39
	v_mov_b32_e32 v43, 0
	s_mov_b32 s16, 1
	s_mov_b32 s17, s15
	v_mov_b32_e32 v49, 0
	ds_read2_b32 v[50:51], v48 offset1:1
	v_add_u32_e32 v48, 8, v48
.LBB0_212:
	s_waitcnt vmcnt(7)
	v_cmp_lt_u32_e64 s[50:51], s16, v0
	v_cmp_lt_u32_e64 s[52:53], s14, v35
	s_add_i32 s16, s16, 2
	s_add_i32 s14, s14, 2
	s_waitcnt lgkmcnt(0)
	v_mov_b32_e32 v228, v50
	v_mov_b32_e32 v229, v51
	ds_read2_b32 v[50:51], v48 offset1:1
	v_cmp_eq_f32_e64 s[58:59], v228, v46
	v_cmp_eq_f32_e64 s[60:61], v229, v37
	v_cmp_gt_f32_e64 s[54:55], v229, v37
	v_cmp_gt_f32_e64 s[56:57], v228, v46
	s_and_b64 s[52:53], s[60:61], s[52:53]
	s_and_b64 s[50:51], s[58:59], s[50:51]
	s_add_i32 s17, s17, -2
	s_or_b64 s[50:51], s[56:57], s[50:51]
	s_or_b64 s[52:53], s[54:55], s[52:53]
	v_add_u32_e32 v48, 8, v48
	v_addc_co_u32_e64 v49, s[52:53], 0, v49, s[52:53]
	s_cmp_lg_u32 s17, 0
	v_addc_co_u32_e64 v43, s[50:51], 0, v43, s[50:51]
	s_cbranch_scc1 .LBB0_212
	s_waitcnt lgkmcnt(0)
	s_cmp_eq_u32 s13, s15
	v_add_u32_e32 v35, v43, v49
	s_cbranch_scc1 .LBB0_216
	s_or_b32 s13, s13, 1
	s_lshl_b32 s14, s13, 2
	s_add_i32 s14, s14, 0x11200
	v_add_u32_e32 v37, s14, v39

.LBB0_218:
	s_or_b64 exec, exec, s[4:5]
	s_and_saveexec_b64 s[4:5], s[48:49]
	s_cbranch_execz .LBB0_227
	v_or_b32_e32 v35, 1, v0
	v_cmp_ne_u32_e64 s[48:49], s10, v35
	s_xor_b64 s[6:7], s[62:63], -1
	s_and_b64 s[14:15], s[6:7], s[48:49]
	v_mov_b32_e32 v41, 2
	s_and_saveexec_b64 s[6:7], s[14:15]
	s_cbranch_execz .LBB0_226
	ds_read_b32 v46, v47 offset:4
	s_add_i32 s13, s10, -1
	s_and_b32 s14, s13, -2
	v_mov_b32_e32 v35, v0
	v_add_u32_e32 v47, 0x11204, v39
	s_waitcnt lgkmcnt(0)
	v_mov_b32_e32 v37, v46
	v_mov_b32_e32 v41, 0
	s_mov_b32 s15, 2
	s_mov_b32 s16, 1
	s_mov_b32 s17, s14
	v_mov_b32_e32 v48, 0
	ds_read2_b32 v[50:51], v47 offset1:1
	v_add_u32_e32 v47, 8, v47
.LBB0_221:
	s_waitcnt vmcnt(7)
	v_cmp_le_u32_e64 s[48:49], s16, v0
	v_cmp_le_u32_e64 s[50:51], s15, v35
	s_add_i32 s16, s16, 2
	s_add_i32 s15, s15, 2
	s_waitcnt lgkmcnt(0)
	v_mov_b32_e32 v228, v50
	v_mov_b32_e32 v229, v51
	ds_read2_b32 v[50:51], v47 offset1:1
	v_cmp_eq_f32_e64 s[56:57], v228, v46
	v_cmp_eq_f32_e64 s[58:59], v229, v37
	v_cmp_gt_f32_e64 s[52:53], v229, v37
	v_cmp_gt_f32_e64 s[54:55], v228, v46
	s_and_b64 s[50:51], s[58:59], s[50:51]
	s_and_b64 s[48:49], s[56:57], s[48:49]
	s_add_i32 s17, s17, -2
	s_or_b64 s[48:49], s[54:55], s[48:49]
	s_or_b64 s[50:51], s[52:53], s[50:51]
	v_add_u32_e32 v47, 8, v47
	v_addc_co_u32_e64 v48, s[50:51], 0, v48, s[50:51]
	s_cmp_lg_u32 s17, 0
	v_addc_co_u32_e64 v41, s[48:49], 0, v41, s[48:49]
	s_cbranch_scc1 .LBB0_221
	s_waitcnt lgkmcnt(0)
	s_cmp_eq_u32 s13, s14
	v_add_u32_e32 v35, v41, v48
	s_cbranch_scc1 .LBB0_225
	s_or_b32 s13, s13, 1
	s_lshl_b32 s14, s13, 2
	s_add_i32 s14, s14, 0x11200
	v_add_u32_e32 v37, s14, v39

.LBB0_227:
	s_or_b64 exec, exec, s[4:5]
	v_mov_b32_e32 v47, 0
	v_mov_b32_e32 v46, 0
	s_and_saveexec_b64 s[4:5], s[46:47]
	s_cbranch_execz .LBB0_236
	v_cmp_ne_u32_e64 s[46:47], s10, v44
	s_xor_b64 s[6:7], s[62:63], -1
	s_and_b64 s[14:15], s[6:7], s[46:47]
	v_mov_b32_e32 v46, 4
	s_and_saveexec_b64 s[6:7], s[14:15]
	s_cbranch_execz .LBB0_235
	v_lshl_add_u32 v35, v0, 2, v45
	ds_read_b32 v46, v35 offset:8
	s_add_i32 s13, s10, -1
	s_and_b32 s15, s13, -2
	s_mov_b32 s14, 2
	v_mov_b32_e32 v35, v44
	s_waitcnt lgkmcnt(0)
	v_mov_b32_e32 v37, v46
	v_add_u32_e32 v49, 0x11204, v39
	v_mov_b32_e32 v48, 0
	s_mov_b32 s16, 1
	s_mov_b32 s17, s15
	v_mov_b32_e32 v50, 0
	ds_read2_b32 v[52:53], v49 offset1:1
	v_add_u32_e32 v49, 8, v49
.LBB0_230:
	s_waitcnt vmcnt(6)
	v_cmp_lt_u32_e64 s[46:47], s16, v44
	v_cmp_lt_u32_e64 s[48:49], s14, v35
	s_add_i32 s16, s16, 2
	s_add_i32 s14, s14, 2
	s_waitcnt lgkmcnt(0)
	v_mov_b32_e32 v228, v52
	v_mov_b32_e32 v229, v53
	ds_read2_b32 v[52:53], v49 offset1:1
	v_cmp_eq_f32_e64 s[54:55], v228, v46
	v_cmp_eq_f32_e64 s[56:57], v229, v37
	v_cmp_gt_f32_e64 s[50:51], v229, v37
	v_cmp_gt_f32_e64 s[52:53], v228, v46
	s_and_b64 s[48:49], s[56:57], s[48:49]
	s_and_b64 s[46:47], s[54:55], s[46:47]
	s_add_i32 s17, s17, -2
	s_or_b64 s[46:47], s[52:53], s[46:47]
	s_or_b64 s[48:49], s[50:51], s[48:49]
	v_add_u32_e32 v49, 8, v49
	v_addc_co_u32_e64 v50, s[48:49], 0, v50, s[48:49]
	s_cmp_lg_u32 s17, 0
	v_addc_co_u32_e64 v48, s[46:47], 0, v48, s[46:47]
	s_cbranch_scc1 .LBB0_230
	s_waitcnt lgkmcnt(0)
	s_cmp_eq_u32 s13, s15
	v_add_u32_e32 v35, v48, v50
	s_cbranch_scc1 .LBB0_234
	s_or_b32 s13, s13, 1
	s_lshl_b32 s14, s13, 2
	s_add_i32 s14, s14, 0x11200
	v_add_u32_e32 v37, s14, v39

.LBB0_236:
	s_or_b64 exec, exec, s[4:5]
	s_and_saveexec_b64 s[4:5], s[44:45]
	s_cbranch_execz .LBB0_245
	v_cmp_ne_u32_e64 s[44:45], s10, v42
	s_xor_b64 s[6:7], s[62:63], -1
	s_and_b64 s[14:15], s[6:7], s[44:45]
	v_mov_b32_e32 v47, 8
	s_and_saveexec_b64 s[6:7], s[14:15]
	s_cbranch_execz .LBB0_244
	v_lshl_add_u32 v35, v0, 2, v45
	ds_read_b32 v44, v35 offset:12
	s_add_i32 s13, s10, -1
	s_and_b32 s15, s13, -2
	s_mov_b32 s14, 2
	v_mov_b32_e32 v35, v42
	s_waitcnt lgkmcnt(0)
	v_mov_b32_e32 v37, v44
	v_add_u32_e32 v48, 0x11204, v39
	v_mov_b32_e32 v47, 0
	s_mov_b32 s16, 1
	s_mov_b32 s17, s15
	v_mov_b32_e32 v49, 0
	ds_read2_b32 v[50:51], v48 offset1:1
	v_add_u32_e32 v48, 8, v48
.LBB0_239:
	s_waitcnt vmcnt(7)
	v_cmp_lt_u32_e64 s[44:45], s16, v42
	v_cmp_lt_u32_e64 s[46:47], s14, v35
	s_add_i32 s16, s16, 2
	s_add_i32 s14, s14, 2
	s_waitcnt lgkmcnt(0)
	v_mov_b32_e32 v228, v50
	v_mov_b32_e32 v229, v51
	ds_read2_b32 v[50:51], v48 offset1:1
	v_cmp_eq_f32_e64 s[52:53], v228, v44
	v_cmp_eq_f32_e64 s[54:55], v229, v37
	v_cmp_gt_f32_e64 s[48:49], v229, v37
	v_cmp_gt_f32_e64 s[50:51], v228, v44
	s_and_b64 s[46:47], s[54:55], s[46:47]
	s_and_b64 s[44:45], s[52:53], s[44:45]
	s_add_i32 s17, s17, -2
	s_or_b64 s[44:45], s[50:51], s[44:45]
	s_or_b64 s[46:47], s[48:49], s[46:47]
	v_add_u32_e32 v48, 8, v48
	v_addc_co_u32_e64 v49, s[46:47], 0, v49, s[46:47]
	s_cmp_lg_u32 s17, 0
	v_addc_co_u32_e64 v47, s[44:45], 0, v47, s[44:45]
	s_cbranch_scc1 .LBB0_239
	s_waitcnt lgkmcnt(0)
	s_cmp_eq_u32 s13, s15
	v_add_u32_e32 v35, v47, v49
	s_cbranch_scc1 .LBB0_243
	s_or_b32 s13, s13, 1
	s_lshl_b32 s14, s13, 2
	s_add_i32 s14, s14, 0x11200
	v_add_u32_e32 v37, s14, v39

.LBB0_245:
	s_or_b64 exec, exec, s[4:5]
	v_mov_b32_e32 v44, 0
	v_mov_b32_e32 v42, 0
	s_and_saveexec_b64 s[4:5], s[42:43]
	s_cbranch_execz .LBB0_254
	v_cmp_ne_u32_e64 s[42:43], s10, v40
	s_xor_b64 s[6:7], s[62:63], -1
	s_and_b64 s[14:15], s[6:7], s[42:43]
	v_mov_b32_e32 v42, 16
	s_and_saveexec_b64 s[6:7], s[14:15]
	s_cbranch_execz .LBB0_253
	v_lshl_add_u32 v35, v0, 2, v45
	ds_read_b32 v42, v35 offset:16
	s_add_i32 s13, s10, -1
	s_and_b32 s15, s13, -2
	s_mov_b32 s14, 2
	v_mov_b32_e32 v35, v40
	s_waitcnt lgkmcnt(0)
	v_mov_b32_e32 v37, v42
	v_add_u32_e32 v49, 0x11204, v39
	v_mov_b32_e32 v48, 0
	s_mov_b32 s16, 1
	s_mov_b32 s17, s15
	v_mov_b32_e32 v50, 0
	ds_read2_b32 v[52:53], v49 offset1:1
	v_add_u32_e32 v49, 8, v49
.LBB0_248:
	s_waitcnt vmcnt(6)
	v_cmp_lt_u32_e64 s[42:43], s16, v40
	v_cmp_lt_u32_e64 s[44:45], s14, v35
	s_add_i32 s16, s16, 2
	s_add_i32 s14, s14, 2
	s_waitcnt lgkmcnt(0)
	v_mov_b32_e32 v228, v52
	v_mov_b32_e32 v229, v53
	ds_read2_b32 v[52:53], v49 offset1:1
	v_cmp_eq_f32_e64 s[50:51], v228, v42
	v_cmp_eq_f32_e64 s[52:53], v229, v37
	v_cmp_gt_f32_e64 s[46:47], v229, v37
	v_cmp_gt_f32_e64 s[48:49], v228, v42
	s_and_b64 s[44:45], s[52:53], s[44:45]
	s_and_b64 s[42:43], s[50:51], s[42:43]
	s_add_i32 s17, s17, -2
	s_or_b64 s[42:43], s[48:49], s[42:43]
	s_or_b64 s[44:45], s[46:47], s[44:45]
	v_add_u32_e32 v49, 8, v49
	v_addc_co_u32_e64 v50, s[44:45], 0, v50, s[44:45]
	s_cmp_lg_u32 s17, 0
	v_addc_co_u32_e64 v48, s[42:43], 0, v48, s[42:43]
	s_cbranch_scc1 .LBB0_248
	s_waitcnt lgkmcnt(0)
	s_cmp_eq_u32 s13, s15
	v_add_u32_e32 v35, v48, v50
	s_cbranch_scc1 .LBB0_252
	s_or_b32 s13, s13, 1
	s_lshl_b32 s14, s13, 2
	s_add_i32 s14, s14, 0x11200
	v_add_u32_e32 v37, s14, v39

.LBB0_254:
	s_or_b64 exec, exec, s[4:5]
	s_and_saveexec_b64 s[4:5], s[40:41]
	s_cbranch_execz .LBB0_263
	v_cmp_ne_u32_e64 s[40:41], s10, v38
	s_xor_b64 s[6:7], s[62:63], -1
	s_and_b64 s[14:15], s[6:7], s[40:41]
	v_mov_b32_e32 v44, 32
	s_and_saveexec_b64 s[6:7], s[14:15]
	s_cbranch_execz .LBB0_262
	v_lshl_add_u32 v35, v0, 2, v45
	ds_read_b32 v40, v35 offset:20
	s_add_i32 s13, s10, -1
	s_and_b32 s15, s13, -2
	s_mov_b32 s14, 2
	v_mov_b32_e32 v35, v38
	s_waitcnt lgkmcnt(0)
	v_mov_b32_e32 v37, v40
	v_add_u32_e32 v48, 0x11204, v39
	v_mov_b32_e32 v44, 0
	s_mov_b32 s16, 1
	s_mov_b32 s17, s15
	v_mov_b32_e32 v49, 0
	ds_read2_b32 v[50:51], v48 offset1:1
	v_add_u32_e32 v48, 8, v48
.LBB0_257:
	s_waitcnt vmcnt(7)
	v_cmp_lt_u32_e64 s[40:41], s16, v38
	v_cmp_lt_u32_e64 s[42:43], s14, v35
	s_add_i32 s16, s16, 2
	s_add_i32 s14, s14, 2
	s_waitcnt lgkmcnt(0)
	v_mov_b32_e32 v228, v50
	v_mov_b32_e32 v229, v51
	ds_read2_b32 v[50:51], v48 offset1:1
	v_cmp_eq_f32_e64 s[48:49], v228, v40
	v_cmp_eq_f32_e64 s[50:51], v229, v37
	v_cmp_gt_f32_e64 s[44:45], v229, v37
	v_cmp_gt_f32_e64 s[46:47], v228, v40
	s_and_b64 s[42:43], s[50:51], s[42:43]
	s_and_b64 s[40:41], s[48:49], s[40:41]
	s_add_i32 s17, s17, -2
	s_or_b64 s[40:41], s[46:47], s[40:41]
	s_or_b64 s[42:43], s[44:45], s[42:43]
	v_add_u32_e32 v48, 8, v48
	v_addc_co_u32_e64 v49, s[42:43], 0, v49, s[42:43]
	s_cmp_lg_u32 s17, 0
	v_addc_co_u32_e64 v44, s[40:41], 0, v44, s[40:41]
	s_cbranch_scc1 .LBB0_257
	s_waitcnt lgkmcnt(0)
	s_cmp_eq_u32 s13, s15
	v_add_u32_e32 v35, v44, v49
	s_cbranch_scc1 .LBB0_261
	s_or_b32 s13, s13, 1
	s_lshl_b32 s14, s13, 2
	s_add_i32 s14, s14, 0x11200
	v_add_u32_e32 v37, s14, v39

.LBB0_263:
	s_or_b64 exec, exec, s[4:5]
	v_mov_b32_e32 v40, 0
	v_mov_b32_e32 v38, 0
	s_and_saveexec_b64 s[4:5], s[38:39]
	s_cbranch_execz .LBB0_272
	v_cmp_ne_u32_e64 s[38:39], s10, v36
	s_xor_b64 s[6:7], s[62:63], -1
	s_and_b64 s[14:15], s[6:7], s[38:39]
	v_mov_b32_e32 v38, 64
	s_and_saveexec_b64 s[6:7], s[14:15]
	s_cbranch_execz .LBB0_271
	v_lshl_add_u32 v35, v0, 2, v45
	ds_read_b32 v38, v35 offset:24
	s_add_i32 s13, s10, -1
	s_and_b32 s15, s13, -2
	s_mov_b32 s14, 2
	v_mov_b32_e32 v35, v36
	s_waitcnt lgkmcnt(0)
	v_mov_b32_e32 v37, v38
	v_add_u32_e32 v49, 0x11204, v39
	v_mov_b32_e32 v48, 0
	s_mov_b32 s16, 1
	s_mov_b32 s17, s15
	v_mov_b32_e32 v50, 0
	ds_read2_b32 v[52:53], v49 offset1:1
	v_add_u32_e32 v49, 8, v49
.LBB0_266:
	s_waitcnt vmcnt(6)
	v_cmp_lt_u32_e64 s[38:39], s16, v36
	v_cmp_lt_u32_e64 s[40:41], s14, v35
	s_add_i32 s16, s16, 2
	s_add_i32 s14, s14, 2
	s_waitcnt lgkmcnt(0)
	v_mov_b32_e32 v228, v52
	v_mov_b32_e32 v229, v53
	ds_read2_b32 v[52:53], v49 offset1:1
	v_cmp_eq_f32_e64 s[46:47], v228, v38
	v_cmp_eq_f32_e64 s[48:49], v229, v37
	v_cmp_gt_f32_e64 s[42:43], v229, v37
	v_cmp_gt_f32_e64 s[44:45], v228, v38
	s_and_b64 s[40:41], s[48:49], s[40:41]
	s_and_b64 s[38:39], s[46:47], s[38:39]
	s_add_i32 s17, s17, -2
	s_or_b64 s[38:39], s[44:45], s[38:39]
	s_or_b64 s[40:41], s[42:43], s[40:41]
	v_add_u32_e32 v49, 8, v49
	v_addc_co_u32_e64 v50, s[40:41], 0, v50, s[40:41]
	s_cmp_lg_u32 s17, 0
	v_addc_co_u32_e64 v48, s[38:39], 0, v48, s[38:39]
	s_cbranch_scc1 .LBB0_266
	s_waitcnt lgkmcnt(0)
	s_cmp_eq_u32 s13, s15
	v_add_u32_e32 v35, v48, v50
	s_cbranch_scc1 .LBB0_270
	s_or_b32 s13, s13, 1
	s_lshl_b32 s14, s13, 2
	s_add_i32 s14, s14, 0x11200
	v_add_u32_e32 v37, s14, v39

.LBB0_272:
	s_or_b64 exec, exec, s[4:5]
	s_and_saveexec_b64 s[4:5], vcc
	s_cbranch_execz .LBB0_281
	v_cmp_ne_u32_e32 vcc, s10, v34
	s_xor_b64 s[6:7], s[62:63], -1
	s_and_b64 s[14:15], s[6:7], vcc
	v_mov_b32_e32 v40, 0x80
	s_and_saveexec_b64 s[6:7], s[14:15]
	s_cbranch_execz .LBB0_280
	v_lshl_add_u32 v0, v0, 2, v45
	ds_read_b32 v0, v0 offset:28
	s_add_i32 s13, s10, -1
	s_and_b32 s15, s13, -2
	s_mov_b32 s14, 2
	v_mov_b32_e32 v35, v34
	s_waitcnt lgkmcnt(0)
	v_mov_b32_e32 v37, v0
	v_add_u32_e32 v40, 0x11204, v39
	v_mov_b32_e32 v36, 0
	s_mov_b32 s16, 1
	s_mov_b32 s17, s15
	v_mov_b32_e32 v45, 0
	ds_read2_b32 v[48:49], v40 offset1:1
	v_add_u32_e32 v40, 8, v40
.LBB0_275:
	v_cmp_lt_u32_e32 vcc, s16, v34
	v_cmp_lt_u32_e64 s[38:39], s14, v35
	s_add_i32 s16, s16, 2
	s_add_i32 s14, s14, 2
	s_waitcnt lgkmcnt(0)
	v_mov_b32_e32 v228, v48
	v_mov_b32_e32 v229, v49
	ds_read2_b32 v[48:49], v40 offset1:1
	v_cmp_eq_f32_e64 s[44:45], v228, v0
	v_cmp_eq_f32_e64 s[46:47], v229, v37
	v_cmp_gt_f32_e64 s[40:41], v229, v37
	v_cmp_gt_f32_e64 s[42:43], v228, v0
	s_and_b64 s[38:39], s[46:47], s[38:39]
	s_and_b64 s[44:45], s[44:45], vcc
	s_add_i32 s17, s17, -2
	s_or_b64 vcc, s[42:43], s[44:45]
	s_or_b64 s[38:39], s[40:41], s[38:39]
	v_add_u32_e32 v40, 8, v40
	v_addc_co_u32_e64 v45, s[38:39], 0, v45, s[38:39]
	s_cmp_lg_u32 s17, 0
	v_addc_co_u32_e32 v36, vcc, 0, v36, vcc
	s_cbranch_scc1 .LBB0_275
	s_waitcnt lgkmcnt(0)
	s_cmp_eq_u32 s13, s15
	v_add_u32_e32 v35, v36, v45
	s_cbranch_scc1 .LBB0_279
	s_or_b32 s13, s13, 1
	s_lshl_b32 s14, s13, 2
	s_add_i32 s14, s14, 0x11200
	v_add_u32_e32 v36, s14, v39

.LBB0_285:
	v_or_b32_e32 v0, s16, v116
	v_mad_u32_u24 v0, v0, s37, v3
	ds_read_b128 v[80:83], v0
	ds_read_b128 v[176:179], v0 offset:32
	ds_read_b128 v[220:223], v0 offset:64
	ds_read_b128 v[224:227], v0 offset:96
	v_mov_b32_e32 v175, v173
	s_waitcnt lgkmcnt(3)
	v_mfma_f32_32x32x16_bf16 v[80:95], v[80:83], v[96:99], 0
	s_waitcnt lgkmcnt(2)
	v_mfma_f32_32x32x16_bf16 v[80:95], v[176:179], v[100:103], v[80:95]
	s_waitcnt lgkmcnt(1)
	v_mfma_f32_32x32x16_bf16 v[80:95], v[220:223], v[104:107], v[80:95]
	s_waitcnt lgkmcnt(0)
	v_mfma_f32_32x32x16_bf16 v[80:95], v[224:227], v[108:111], v[80:95]
	s_nop 11
	v_max_f32_e32 v0, v81, v81
	v_max_f32_e32 v2, v80, v80
	v_max_f32_e32 v0, v2, v0
	v_max3_f32 v0, v0, v82, v83
	v_max3_f32 v0, v0, v84, v85
	v_max3_f32 v0, v0, v86, v87
	v_max3_f32 v0, v0, v88, v89
	v_max3_f32 v0, v0, v90, v91
	v_max3_f32 v0, v0, v92, v93
	v_max3_f32 v0, v0, v94, v95
	v_cndmask_b32_e64 v0, v0, v202, s[38:39]
	ds_bpermute_b32 v2, v119, v0
	s_waitcnt lgkmcnt(0)
	v_max3_f32 v173, v175, v0, v2
	v_sub_f32_e32 v0, v175, v173
	v_exp_f32_e32 v0, v0
	v_cmp_eq_f32_e32 vcc, v173, v175
	s_cmp_eq_u64 vcc, exec
	s_cbranch_scc1 .LBB0_287
	v_pk_mul_f32 v[78:79], v[78:79], v[0:1] op_sel_hi:[1,0]
	v_pk_mul_f32 v[76:77], v[76:77], v[0:1] op_sel_hi:[1,0]
	v_pk_mul_f32 v[74:75], v[74:75], v[0:1] op_sel_hi:[1,0]
	v_pk_mul_f32 v[72:73], v[72:73], v[0:1] op_sel_hi:[1,0]
	v_pk_mul_f32 v[70:71], v[70:71], v[0:1] op_sel_hi:[1,0]
	v_pk_mul_f32 v[68:69], v[68:69], v[0:1] op_sel_hi:[1,0]
	v_pk_mul_f32 v[66:67], v[66:67], v[0:1] op_sel_hi:[1,0]
	v_pk_mul_f32 v[64:65], v[64:65], v[0:1] op_sel_hi:[1,0]
	v_pk_mul_f32 v[62:63], v[62:63], v[0:1] op_sel_hi:[1,0]
	v_pk_mul_f32 v[60:61], v[60:61], v[0:1] op_sel_hi:[1,0]
	v_pk_mul_f32 v[58:59], v[58:59], v[0:1] op_sel_hi:[1,0]
	v_pk_mul_f32 v[56:57], v[56:57], v[0:1] op_sel_hi:[1,0]
	v_pk_mul_f32 v[54:55], v[54:55], v[0:1] op_sel_hi:[1,0]
	v_pk_mul_f32 v[52:53], v[52:53], v[0:1] op_sel_hi:[1,0]
	v_pk_mul_f32 v[50:51], v[50:51], v[0:1] op_sel_hi:[1,0]
	v_pk_mul_f32 v[48:49], v[48:49], v[0:1] op_sel_hi:[1,0]

.LBB0_291:
	v_or_b32_e32 v0, s16, v116
	v_mad_u32_u24 v0, v0, s37, v3
	s_nop 4
	ds_read_b128 v[48:51], v0
	ds_read_b128 v[64:67], v0 offset:32
	ds_read_b128 v[220:223], v0 offset:64
	ds_read_b128 v[224:227], v0 offset:96
	s_or_b32 s6, s16, s15
	v_cmp_le_i32_e32 vcc, s6, v159
	s_or_b32 s7, s6, 2
	s_waitcnt lgkmcnt(3)
	v_mfma_f32_32x32x16_bf16 v[48:63], v[48:51], v[96:99], 0
	s_waitcnt lgkmcnt(2)
	v_mfma_f32_32x32x16_bf16 v[48:63], v[64:67], v[100:103], v[48:63]
	s_waitcnt lgkmcnt(1)
	v_mfma_f32_32x32x16_bf16 v[48:63], v[220:223], v[104:107], v[48:63]
	s_waitcnt lgkmcnt(0)
	v_mfma_f32_32x32x16_bf16 v[48:63], v[224:227], v[108:111], v[48:63]
	s_nop 11
	v_cndmask_b32_e32 v48, v202, v48, vcc
	v_cmp_lt_i32_e32 vcc, s6, v159
	s_nop 1
	v_cndmask_b32_e32 v2, v202, v49, vcc
	v_cmp_le_i32_e32 vcc, s7, v159
	s_or_b32 s7, s6, 3
	v_max_f32_e32 v0, v2, v2
	v_cndmask_b32_e32 v49, v202, v50, vcc
	v_cmp_le_i32_e32 vcc, s7, v159
	s_or_b32 s7, s6, 8
	s_nop 0
	v_cndmask_b32_e32 v50, v202, v51, vcc
	v_cmp_le_i32_e32 vcc, s7, v159
	s_or_b32 s7, s6, 9
	s_nop 0
	v_cndmask_b32_e32 v51, v202, v52, vcc
	v_cmp_le_i32_e32 vcc, s7, v159
	s_or_b32 s7, s6, 10
	s_nop 0
	v_cndmask_b32_e32 v52, v202, v53, vcc
	v_cmp_le_i32_e32 vcc, s7, v159
	s_or_b32 s7, s6, 11
	s_nop 0
	v_cndmask_b32_e32 v54, v202, v54, vcc
	v_cmp_le_i32_e32 vcc, s7, v159
	s_or_b32 s7, s6, 16
	s_nop 0
	v_cndmask_b32_e32 v53, v202, v55, vcc
	v_cmp_le_i32_e32 vcc, s7, v159
	s_or_b32 s7, s6, 17
	s_nop 0
	v_cndmask_b32_e32 v55, v202, v56, vcc
	v_cmp_le_i32_e32 vcc, s7, v159
	s_or_b32 s7, s6, 18
	s_nop 0
	v_cndmask_b32_e32 v56, v202, v57, vcc
	v_cmp_le_i32_e32 vcc, s7, v159
	s_or_b32 s7, s6, 19
	s_nop 0
	v_cndmask_b32_e32 v57, v202, v58, vcc
	v_cmp_le_i32_e32 vcc, s7, v159
	s_or_b32 s7, s6, 24
	s_nop 0
	v_cndmask_b32_e32 v64, v202, v59, vcc
	v_cmp_le_i32_e32 vcc, s7, v159
	s_or_b32 s7, s6, 25
	s_nop 0
	v_cndmask_b32_e32 v65, v202, v60, vcc
	v_cmp_le_i32_e32 vcc, s7, v159
	s_or_b32 s7, s6, 26
	s_or_b32 s6, s6, 27
	v_cndmask_b32_e32 v59, v202, v61, vcc
	v_max_f32_e32 v61, v48, v48
	v_max_f32_e32 v0, v61, v0
	v_max3_f32 v0, v0, v49, v50
	v_max3_f32 v0, v0, v51, v52
	v_max3_f32 v0, v0, v54, v53
	v_cmp_le_i32_e32 vcc, s7, v159
	v_max3_f32 v0, v0, v55, v56
	v_max3_f32 v0, v0, v57, v64
	v_cndmask_b32_e32 v60, v202, v62, vcc
	v_cmp_le_i32_e32 vcc, s6, v159
	v_max3_f32 v0, v0, v65, v59
	v_mov_b32_e32 v62, v167
	v_cndmask_b32_e32 v58, v202, v63, vcc
	v_max3_f32 v0, v0, v60, v58
	v_cndmask_b32_e64 v0, v0, v202, s[38:39]
	ds_bpermute_b32 v61, v119, v0
	s_waitcnt lgkmcnt(0)
	v_max3_f32 v167, v62, v0, v61
	v_sub_f32_e32 v0, v62, v167
	v_exp_f32_e32 v0, v0
	v_cmp_eq_f32_e32 vcc, v167, v62
	s_cmp_eq_u64 vcc, exec
	s_cbranch_scc1 .LBB0_293
	v_pk_mul_f32 v[46:47], v[46:47], v[0:1] op_sel_hi:[1,0]
	v_pk_mul_f32 v[44:45], v[44:45], v[0:1] op_sel_hi:[1,0]
	v_pk_mul_f32 v[42:43], v[42:43], v[0:1] op_sel_hi:[1,0]
	v_pk_mul_f32 v[40:41], v[40:41], v[0:1] op_sel_hi:[1,0]
	v_pk_mul_f32 v[38:39], v[38:39], v[0:1] op_sel_hi:[1,0]
	v_pk_mul_f32 v[36:37], v[36:37], v[0:1] op_sel_hi:[1,0]
	v_pk_mul_f32 v[34:35], v[34:35], v[0:1] op_sel_hi:[1,0]
	v_pk_mul_f32 v[32:33], v[32:33], v[0:1] op_sel_hi:[1,0]
	v_pk_mul_f32 v[30:31], v[30:31], v[0:1] op_sel_hi:[1,0]
	v_pk_mul_f32 v[28:29], v[28:29], v[0:1] op_sel_hi:[1,0]
	v_pk_mul_f32 v[26:27], v[26:27], v[0:1] op_sel_hi:[1,0]
	v_pk_mul_f32 v[24:25], v[24:25], v[0:1] op_sel_hi:[1,0]
	v_pk_mul_f32 v[22:23], v[22:23], v[0:1] op_sel_hi:[1,0]
	v_pk_mul_f32 v[20:21], v[20:21], v[0:1] op_sel_hi:[1,0]
	v_pk_mul_f32 v[18:19], v[18:19], v[0:1] op_sel_hi:[1,0]
	v_pk_mul_f32 v[16:17], v[16:17], v[0:1] op_sel_hi:[1,0]

.LBB0_303:
	v_or_b32_e32 v0, s6, v117
	v_mad_u32_u24 v0, v0, s37, v14
	ds_read_b128 v[80:83], v0
	ds_read_b128 v[174:177], v0 offset:32
	ds_read_b128 v[220:223], v0 offset:64
	ds_read_b128 v[224:227], v0 offset:96
	s_waitcnt lgkmcnt(3)
	v_mfma_f32_32x32x16_bf16 v[80:95], v[80:83], v[96:99], 0
	s_waitcnt lgkmcnt(2)
	v_mfma_f32_32x32x16_bf16 v[80:95], v[174:177], v[100:103], v[80:95]
	s_waitcnt lgkmcnt(1)
	v_mfma_f32_32x32x16_bf16 v[80:95], v[220:223], v[104:107], v[80:95]
	v_or_b32_e32 v0, s6, v171
	v_cmp_le_i32_e32 vcc, v0, v126
	v_cmp_gt_i32_e64 s[38:39], v0, v156
	s_and_b64 vcc, vcc, s[38:39]
	v_cmp_ge_i32_e64 s[38:39], v0, v156
	v_or_b32_e32 v173, 2, v0
	s_waitcnt lgkmcnt(0)
	v_mfma_f32_32x32x16_bf16 v[80:95], v[224:227], v[108:111], v[80:95]
	s_nop 11
	v_cndmask_b32_e32 v80, v202, v80, vcc
	v_cmp_lt_i32_e32 vcc, v0, v126
	s_and_b64 vcc, vcc, s[38:39]
	v_cmp_gt_i32_e64 s[38:39], v173, v156
	v_cndmask_b32_e32 v81, v202, v81, vcc
	v_cmp_le_i32_e32 vcc, v173, v126
	s_and_b64 vcc, vcc, s[38:39]
	v_or_b32_e32 v173, 3, v0
	v_cndmask_b32_e32 v82, v202, v82, vcc
	v_cmp_le_i32_e32 vcc, v173, v126
	v_cmp_gt_i32_e64 s[38:39], v173, v156
	s_and_b64 vcc, vcc, s[38:39]
	v_or_b32_e32 v173, 8, v0
	v_cndmask_b32_e32 v83, v202, v83, vcc
	v_cmp_le_i32_e32 vcc, v173, v126
	v_cmp_gt_i32_e64 s[38:39], v173, v156
	s_and_b64 vcc, vcc, s[38:39]
	v_or_b32_e32 v173, 9, v0
	v_cndmask_b32_e32 v84, v202, v84, vcc
	v_cmp_le_i32_e32 vcc, v173, v126
	v_cmp_gt_i32_e64 s[38:39], v173, v156
	s_and_b64 vcc, vcc, s[38:39]
	v_cndmask_b32_e32 v173, v202, v85, vcc
	v_or_b32_e32 v85, 10, v0
	v_cmp_le_i32_e32 vcc, v85, v126
	v_cmp_gt_i32_e64 s[38:39], v85, v156
	s_and_b64 vcc, vcc, s[38:39]
	v_or_b32_e32 v85, 11, v0
	v_cndmask_b32_e32 v177, v202, v86, vcc
	v_cmp_le_i32_e32 vcc, v85, v126
	v_cmp_gt_i32_e64 s[38:39], v85, v156
	s_and_b64 vcc, vcc, s[38:39]
	v_or_b32_e32 v85, 16, v0
	v_cndmask_b32_e32 v175, v202, v87, vcc
	v_cmp_le_i32_e32 vcc, v85, v126
	v_cmp_gt_i32_e64 s[38:39], v85, v156
	s_and_b64 vcc, vcc, s[38:39]
	v_or_b32_e32 v85, 17, v0
	v_cndmask_b32_e32 v176, v202, v88, vcc
	v_cmp_le_i32_e32 vcc, v85, v126
	v_cmp_gt_i32_e64 s[38:39], v85, v156
	s_and_b64 vcc, vcc, s[38:39]
	v_or_b32_e32 v85, 18, v0
	v_cndmask_b32_e32 v89, v202, v89, vcc
	v_cmp_le_i32_e32 vcc, v85, v126
	v_cmp_gt_i32_e64 s[38:39], v85, v156
	s_and_b64 vcc, vcc, s[38:39]
	v_or_b32_e32 v85, 19, v0
	v_cndmask_b32_e32 v174, v202, v90, vcc
	v_cmp_le_i32_e32 vcc, v85, v126
	v_cmp_gt_i32_e64 s[38:39], v85, v156
	s_and_b64 vcc, vcc, s[38:39]
	v_or_b32_e32 v85, 24, v0
	v_cndmask_b32_e32 v88, v202, v91, vcc
	v_cmp_le_i32_e32 vcc, v85, v126
	v_cmp_gt_i32_e64 s[38:39], v85, v156
	s_and_b64 vcc, vcc, s[38:39]
	v_or_b32_e32 v85, 25, v0
	v_cndmask_b32_e32 v90, v202, v92, vcc
	v_cmp_le_i32_e32 vcc, v85, v126
	v_cmp_gt_i32_e64 s[38:39], v85, v156
	s_and_b64 vcc, vcc, s[38:39]
	v_or_b32_e32 v86, 26, v0
	v_cndmask_b32_e32 v85, v202, v93, vcc
	v_cmp_le_i32_e32 vcc, v86, v126
	v_cmp_gt_i32_e64 s[38:39], v86, v156
	s_and_b64 vcc, vcc, s[38:39]
	v_or_b32_e32 v0, 27, v0
	v_cndmask_b32_e32 v87, v202, v94, vcc
	v_cmp_le_i32_e32 vcc, v0, v126
	v_cmp_gt_i32_e64 s[38:39], v0, v156
	v_max_f32_e32 v0, v81, v81
	v_max_f32_e32 v91, v80, v80
	v_max_f32_e32 v0, v91, v0
	v_max3_f32 v0, v0, v82, v83
	v_max3_f32 v0, v0, v84, v173
	v_max3_f32 v0, v0, v177, v175
	v_max3_f32 v0, v0, v176, v89
	s_and_b64 vcc, vcc, s[38:39]
	v_max3_f32 v0, v0, v174, v88
	v_cndmask_b32_e32 v86, v202, v95, vcc
	v_max3_f32 v0, v0, v90, v85
	v_max3_f32 v0, v0, v87, v86
	ds_bpermute_b32 v91, v119, v0
	v_mov_b32_e32 v92, v170
	s_waitcnt lgkmcnt(0)
	v_max3_f32 v170, v92, v0, v91
	v_sub_f32_e32 v0, v92, v170
	v_exp_f32_e32 v0, v0
	v_cmp_eq_f32_e32 vcc, v170, v92
	s_cmp_eq_u64 vcc, exec
	s_cbranch_scc1 .LBB0_305
	v_pk_mul_f32 v[62:63], v[62:63], v[0:1] op_sel_hi:[1,0]
	v_pk_mul_f32 v[60:61], v[60:61], v[0:1] op_sel_hi:[1,0]
	v_pk_mul_f32 v[58:59], v[58:59], v[0:1] op_sel_hi:[1,0]
	v_pk_mul_f32 v[56:57], v[56:57], v[0:1] op_sel_hi:[1,0]
	v_pk_mul_f32 v[54:55], v[54:55], v[0:1] op_sel_hi:[1,0]
	v_pk_mul_f32 v[52:53], v[52:53], v[0:1] op_sel_hi:[1,0]
	v_pk_mul_f32 v[50:51], v[50:51], v[0:1] op_sel_hi:[1,0]
	v_pk_mul_f32 v[48:49], v[48:49], v[0:1] op_sel_hi:[1,0]
	v_pk_mul_f32 v[78:79], v[78:79], v[0:1] op_sel_hi:[1,0]
	v_pk_mul_f32 v[76:77], v[76:77], v[0:1] op_sel_hi:[1,0]
	v_pk_mul_f32 v[74:75], v[74:75], v[0:1] op_sel_hi:[1,0]
	v_pk_mul_f32 v[72:73], v[72:73], v[0:1] op_sel_hi:[1,0]
	v_pk_mul_f32 v[70:71], v[70:71], v[0:1] op_sel_hi:[1,0]
	v_pk_mul_f32 v[68:69], v[68:69], v[0:1] op_sel_hi:[1,0]
	v_pk_mul_f32 v[66:67], v[66:67], v[0:1] op_sel_hi:[1,0]
	v_pk_mul_f32 v[64:65], v[64:65], v[0:1] op_sel_hi:[1,0]

.LBB0_309:
	v_or_b32_e32 v0, s15, v117
	v_mad_u32_u24 v0, v0, s37, v14
	ds_read_b128 v[48:51], v0
	s_nop 3
	ds_read_b128 v[64:67], v0 offset:32
	ds_read_b128 v[220:223], v0 offset:64
	ds_read_b128 v[224:227], v0 offset:96
	s_waitcnt lgkmcnt(3)
	v_mfma_f32_32x32x16_bf16 v[48:63], v[48:51], v[96:99], 0
	s_waitcnt lgkmcnt(2)
	v_mfma_f32_32x32x16_bf16 v[48:63], v[64:67], v[100:103], v[48:63]
	s_waitcnt lgkmcnt(1)
	v_mfma_f32_32x32x16_bf16 v[48:63], v[220:223], v[104:107], v[48:63]
	s_waitcnt lgkmcnt(0)
	v_mfma_f32_32x32x16_bf16 v[48:63], v[224:227], v[108:111], v[48:63]
	v_mov_b32_e32 v65, v168
	s_nop 10
	v_max_f32_e32 v0, v49, v49
	v_max_f32_e32 v64, v48, v48
	v_max_f32_e32 v0, v64, v0
	v_max3_f32 v0, v0, v50, v51
	v_max3_f32 v0, v0, v52, v53
	v_max3_f32 v0, v0, v54, v55
	v_max3_f32 v0, v0, v56, v57
	v_max3_f32 v0, v0, v58, v59
	v_max3_f32 v0, v0, v60, v61
	v_max3_f32 v0, v0, v62, v63
	ds_bpermute_b32 v64, v119, v0
	s_waitcnt lgkmcnt(0)
	v_max3_f32 v168, v65, v0, v64
	v_sub_f32_e32 v0, v65, v168
	v_exp_f32_e32 v0, v0
	v_cmp_eq_f32_e32 vcc, v168, v65
	s_cmp_eq_u64 vcc, exec
	s_cbranch_scc1 .LBB0_311
	v_pk_mul_f32 v[46:47], v[46:47], v[0:1] op_sel_hi:[1,0]
	v_pk_mul_f32 v[44:45], v[44:45], v[0:1] op_sel_hi:[1,0]
	v_pk_mul_f32 v[42:43], v[42:43], v[0:1] op_sel_hi:[1,0]
	v_pk_mul_f32 v[40:41], v[40:41], v[0:1] op_sel_hi:[1,0]
	v_pk_mul_f32 v[38:39], v[38:39], v[0:1] op_sel_hi:[1,0]
	v_pk_mul_f32 v[36:37], v[36:37], v[0:1] op_sel_hi:[1,0]
	v_pk_mul_f32 v[34:35], v[34:35], v[0:1] op_sel_hi:[1,0]
	v_pk_mul_f32 v[32:33], v[32:33], v[0:1] op_sel_hi:[1,0]
	v_pk_mul_f32 v[30:31], v[30:31], v[0:1] op_sel_hi:[1,0]
	v_pk_mul_f32 v[28:29], v[28:29], v[0:1] op_sel_hi:[1,0]
	v_pk_mul_f32 v[26:27], v[26:27], v[0:1] op_sel_hi:[1,0]
	v_pk_mul_f32 v[24:25], v[24:25], v[0:1] op_sel_hi:[1,0]
	v_pk_mul_f32 v[22:23], v[22:23], v[0:1] op_sel_hi:[1,0]
	v_pk_mul_f32 v[20:21], v[20:21], v[0:1] op_sel_hi:[1,0]
	v_pk_mul_f32 v[18:19], v[18:19], v[0:1] op_sel_hi:[1,0]
	v_pk_mul_f32 v[16:17], v[16:17], v[0:1] op_sel_hi:[1,0]

.LBB0_332:
	s_or_b64 exec, exec, s[4:5]
	s_waitcnt lgkmcnt(0)
	s_barrier
	ds_read_b32 v0, v186
	s_waitcnt lgkmcnt(0)
	v_readfirstlane_b32 s4, v0
	s_cmpk_gt_i32 s4, 0xff
	s_cbranch_scc1 .LBB0_153
	v_mov_b32_e32 v10, v133
	s_ashr_i32 s8, s4, 5
	v_and_b32_e32 v6, 63, v10
	s_bfe_u32 s6, s4, 0x30002
	s_lshl_b32 s4, s4, 4
	s_and_b32 s5, s4, 48
	v_lshl_or_b32 v2, s6, 6, v6
	s_mul_i32 s4, s78, 0x680
	v_add_u32_e32 v4, s4, v2
	v_readlane_b32 s40, v252, 31
	v_ashrrev_i32_e32 v5, 31, v4
	v_readlane_b32 s52, v252, 43
	v_readlane_b32 s53, v252, 44
	v_readlane_b32 s41, v252, 32
	v_readlane_b32 s42, v252, 33
	v_lshl_add_u64 v[12:13], v[4:5], 2, s[52:53]
	v_add_u32_e32 v4, 0x400, v4
	v_ashrrev_i32_e32 v5, 31, v4
	v_lshl_add_u64 v[4:5], v[4:5], 2, s[52:53]
	v_readlane_b32 s43, v252, 34
	v_readlane_b32 s44, v252, 35
	v_readlane_b32 s45, v252, 36
	v_readlane_b32 s46, v252, 37
	v_readlane_b32 s47, v252, 38
	v_readlane_b32 s48, v252, 39
	v_readlane_b32 s49, v252, 40
	v_readlane_b32 s50, v252, 41
	v_readlane_b32 s51, v252, 42
	v_readlane_b32 s54, v252, 45
	v_readlane_b32 s55, v252, 46
	global_load_dword v3, v[12:13], off
	global_load_dword v16, v[12:13], off offset:2048
	global_load_dword v17, v[4:5], off
	v_or_b32_e32 v4, s19, v2
	v_ashrrev_i32_e32 v7, 6, v10
	v_ashrrev_i32_e32 v5, 31, v4
	v_readlane_b32 s40, v252, 47
	v_lshlrev_b32_e32 v8, 2, v7
	v_lshlrev_b64 v[4:5], 2, v[4:5]
	v_readlane_b32 s46, v252, 53
	v_readlane_b32 s47, v252, 54
	v_readlane_b32 s48, v252, 55
	v_readlane_b32 s49, v252, 56
	v_lshl_add_u64 v[12:13], s[46:47], 0, v[4:5]
	s_ashr_i32 s9, s8, 31
	v_max_i32_e32 v9, 1, v8
	global_load_dword v18, v[12:13], off
	v_lshl_add_u64 v[4:5], s[48:49], 0, v[4:5]
	s_lshl_b64 s[56:57], s[8:9], 12
	v_lshlrev_b32_e32 v0, 1, v2
	v_add_u32_e32 v12, -1, v9
	v_mov_b32_e32 v13, v1
	global_load_dword v19, v[4:5], off
	v_lshl_add_u64 v[4:5], s[88:89], 0, v[0:1]
	v_lshl_add_u64 v[12:13], s[56:57], 0, v[12:13]
	v_mad_u64_u32 v[14:15], s[8:9], v12, s29, v[4:5]
	v_mad_i32_i24 v15, v13, s29, v15
	v_max_i32_e32 v12, 0, v8
	v_mov_b32_e32 v13, v1
	v_lshl_add_u64 v[12:13], s[56:57], 0, v[12:13]
	global_load_ushort v11, v[14:15], off
	global_load_ushort v38, v[14:15], off offset:1024
	global_load_ushort v39, v[14:15], off offset:2048
	v_mad_u64_u32 v[14:15], s[8:9], v12, s29, v[4:5]
	v_max_i32_e32 v9, -1, v8
	v_mad_i32_i24 v15, v13, s29, v15
	v_add_u32_e32 v12, 1, v9
	v_mov_b32_e32 v13, v1
	v_lshl_add_u64 v[12:13], s[56:57], 0, v[12:13]
	global_load_ushort v40, v[14:15], off
	global_load_ushort v41, v[14:15], off offset:1024
	global_load_ushort v42, v[14:15], off offset:2048
	v_mad_u64_u32 v[14:15], s[8:9], v12, s29, v[4:5]
	v_max_i32_e32 v9, -2, v8
	v_mad_i32_i24 v15, v13, s29, v15
	v_add_u32_e32 v12, 2, v9
	v_mov_b32_e32 v13, v1
	v_lshl_add_u64 v[12:13], s[56:57], 0, v[12:13]
	global_load_ushort v54, v[14:15], off
	global_load_ushort v55, v[14:15], off offset:1024
	global_load_ushort v56, v[14:15], off offset:2048
	v_mad_u64_u32 v[14:15], s[8:9], v12, s29, v[4:5]
	v_max_i32_e32 v9, -3, v8
	v_mad_i32_i24 v15, v13, s29, v15
	v_add_u32_e32 v12, 3, v9
	v_mov_b32_e32 v13, v1
	v_lshl_add_u64 v[12:13], s[56:57], 0, v[12:13]
	global_load_ushort v59, v[14:15], off
	global_load_ushort v60, v[14:15], off offset:1024
	global_load_ushort v63, v[14:15], off offset:2048
	v_mad_u64_u32 v[14:15], s[8:9], v12, s29, v[4:5]
	v_ashrrev_i32_e32 v9, 31, v8
	v_mad_i32_i24 v15, v13, s29, v15
	v_lshl_add_u64 v[12:13], s[56:57], 0, v[8:9]
	global_load_ushort v65, v[14:15], off
	global_load_ushort v69, v[14:15], off offset:1024
	global_load_ushort v70, v[14:15], off offset:2048
	v_lshlrev_b64 v[14:15], 10, v[12:13]
	s_lshl_b32 s4, s6, 2
	v_or_b32_e32 v14, v14, v0
	s_add_u32 s58, s64, s4
	v_lshl_add_u64 v[20:21], s[0:1], 0, v[14:15]
	v_lshl_add_u64 v[14:15], s[24:25], 0, v[14:15]
	s_addc_u32 s59, s65, 0
	global_load_ushort v9, v[20:21], off
	v_cmp_gt_i32_e32 vcc, 1, v7
	global_load_ushort v20, v[14:15], off
	v_lshlrev_b64 v[14:15], 5, v[12:13]
	v_lshl_add_u64 v[14:15], s[58:59], 0, v[14:15]
	global_load_dword v21, v[14:15], off
	v_or_b32_e32 v14, 1, v12
	v_mov_b32_e32 v15, v13
	v_lshlrev_b64 v[24:25], 10, v[14:15]
	v_or_b32_e32 v24, v24, v0
	v_lshlrev_b64 v[14:15], 5, v[14:15]
	v_lshl_add_u64 v[22:23], s[0:1], 0, v[24:25]
	v_lshl_add_u64 v[24:25], s[24:25], 0, v[24:25]
	v_lshl_add_u64 v[14:15], s[58:59], 0, v[14:15]
	global_load_ushort v22, v[22:23], off
	v_and_b32_e32 v31, 15, v10
	global_load_ushort v23, v[24:25], off
	s_mov_b32 s4, 0
	global_load_dword v24, v[14:15], off
	v_or_b32_e32 v14, 2, v12
	v_mov_b32_e32 v15, v13
	v_lshlrev_b64 v[26:27], 10, v[14:15]
	v_or_b32_e32 v26, v26, v0
	v_lshlrev_b64 v[14:15], 5, v[14:15]
	v_lshl_add_u64 v[28:29], s[0:1], 0, v[26:27]
	v_lshl_add_u64 v[26:27], s[24:25], 0, v[26:27]
	v_lshl_add_u64 v[14:15], s[58:59], 0, v[14:15]
	v_or_b32_e32 v12, 3, v12
	global_load_ushort v25, v[28:29], off
	v_readlane_b32 s41, v252, 48
	global_load_ushort v27, v[26:27], off
	v_readlane_b32 s42, v252, 49
	global_load_dword v26, v[14:15], off
	v_lshlrev_b64 v[14:15], 10, v[12:13]
	v_or_b32_e32 v14, v14, v0
	v_lshlrev_b64 v[12:13], 5, v[12:13]
	v_lshl_add_u64 v[28:29], s[0:1], 0, v[14:15]
	v_lshl_add_u64 v[14:15], s[24:25], 0, v[14:15]
	v_lshl_add_u64 v[12:13], s[58:59], 0, v[12:13]
	global_load_ushort v28, v[28:29], off
	s_waitcnt vmcnt(24)
	v_cndmask_b32_e64 v62, v11, 0, vcc
	global_load_ushort v29, v[14:15], off
	global_load_dword v30, v[12:13], off
	v_add_u32_e32 v12, 16, v8
	v_max_i32_e32 v13, 1, v12
	v_add_u32_e32 v14, -1, v13
	v_mov_b32_e32 v15, v1
	v_lshl_add_u64 v[14:15], s[56:57], 0, v[14:15]
	v_mad_u64_u32 v[32:33], s[8:9], v14, s29, v[4:5]
	v_mad_i32_i24 v33, v15, s29, v33
	v_max_i32_e32 v14, 0, v12
	v_mov_b32_e32 v15, v1
	v_lshl_add_u64 v[14:15], s[56:57], 0, v[14:15]
	global_load_ushort v71, v[32:33], off
	global_load_ushort v72, v[32:33], off offset:1024
	global_load_ushort v73, v[32:33], off offset:2048
	v_mad_u64_u32 v[32:33], s[8:9], v14, s29, v[4:5]
	v_max_i32_e32 v13, -1, v12
	v_mad_i32_i24 v33, v15, s29, v33
	v_add_u32_e32 v14, 1, v13
	v_mov_b32_e32 v15, v1
	v_lshl_add_u64 v[14:15], s[56:57], 0, v[14:15]
	global_load_ushort v74, v[32:33], off
	global_load_ushort v75, v[32:33], off offset:1024
	global_load_ushort v76, v[32:33], off offset:2048
	v_mad_u64_u32 v[32:33], s[8:9], v14, s29, v[4:5]
	v_max_i32_e32 v13, -2, v12
	v_mad_i32_i24 v33, v15, s29, v33
	v_add_u32_e32 v14, 2, v13
	v_mov_b32_e32 v15, v1
	v_lshl_add_u64 v[14:15], s[56:57], 0, v[14:15]
	global_load_ushort v77, v[32:33], off
	global_load_ushort v83, v[32:33], off offset:1024
	global_load_ushort v84, v[32:33], off offset:2048
	v_mad_u64_u32 v[32:33], s[8:9], v14, s29, v[4:5]
	v_max_i32_e32 v13, -3, v12
	v_mad_i32_i24 v33, v15, s29, v33
	v_add_u32_e32 v14, 3, v13
	v_mov_b32_e32 v15, v1
	v_lshl_add_u64 v[14:15], s[56:57], 0, v[14:15]
	global_load_ushort v85, v[32:33], off
	global_load_ushort v86, v[32:33], off offset:1024
	global_load_ushort v87, v[32:33], off offset:2048
	v_mad_u64_u32 v[32:33], s[8:9], v14, s29, v[4:5]
	v_ashrrev_i32_e32 v13, 31, v12
	v_mad_i32_i24 v33, v15, s29, v33
	v_lshl_add_u64 v[12:13], s[56:57], 0, v[12:13]
	global_load_ushort v90, v[32:33], off
	global_load_ushort v91, v[32:33], off offset:1024
	global_load_ushort v92, v[32:33], off offset:2048
	v_lshlrev_b64 v[32:33], 10, v[12:13]
	v_or_b32_e32 v32, v32, v0
	v_lshl_add_u64 v[14:15], s[0:1], 0, v[32:33]
	v_lshl_add_u64 v[32:33], s[24:25], 0, v[32:33]
	global_load_ushort v15, v[14:15], off
	s_waitcnt vmcnt(41)
	v_cndmask_b32_e64 v67, v38, 0, vcc
	global_load_ushort v43, v[32:33], off
	v_lshlrev_b64 v[32:33], 5, v[12:13]
	v_lshl_add_u64 v[32:33], s[58:59], 0, v[32:33]
	global_load_dword v44, v[32:33], off
	v_or_b32_e32 v32, 1, v12
	v_mov_b32_e32 v33, v13
	v_lshlrev_b64 v[34:35], 10, v[32:33]
	v_or_b32_e32 v34, v34, v0
	v_lshlrev_b64 v[32:33], 5, v[32:33]
	v_lshl_add_u64 v[36:37], s[0:1], 0, v[34:35]
	v_lshl_add_u64 v[34:35], s[24:25], 0, v[34:35]
	v_lshl_add_u64 v[32:33], s[58:59], 0, v[32:33]
	global_load_ushort v48, v[36:37], off
	global_load_ushort v49, v[34:35], off
	global_load_dword v46, v[32:33], off
	v_or_b32_e32 v32, 2, v12
	v_mov_b32_e32 v33, v13
	v_lshlrev_b64 v[34:35], 10, v[32:33]
	v_or_b32_e32 v34, v34, v0
	v_lshlrev_b64 v[32:33], 5, v[32:33]
	v_lshl_add_u64 v[36:37], s[0:1], 0, v[34:35]
	v_lshl_add_u64 v[34:35], s[24:25], 0, v[34:35]
	v_lshl_add_u64 v[32:33], s[58:59], 0, v[32:33]
	v_or_b32_e32 v12, 3, v12
	global_load_ushort v45, v[36:37], off
	global_load_ushort v47, v[34:35], off
	global_load_dword v52, v[32:33], off
	v_lshlrev_b64 v[32:33], 10, v[12:13]
	v_or_b32_e32 v32, v32, v0
	v_lshlrev_b64 v[12:13], 5, v[12:13]
	v_lshl_add_u64 v[34:35], s[0:1], 0, v[32:33]
	v_lshl_add_u64 v[32:33], s[24:25], 0, v[32:33]
	v_lshl_add_u64 v[12:13], s[58:59], 0, v[12:13]
	global_load_ushort v50, v[34:35], off
	global_load_ushort v51, v[32:33], off
	global_load_dword v53, v[12:13], off
	s_waitcnt vmcnt(51)
	v_cndmask_b32_e64 v66, v39, 0, vcc
	v_cmp_gt_i32_e32 vcc, 0, v7
	v_add_u32_e32 v0, s5, v8
	v_bfe_u32 v12, v10, 4, 2
	s_waitcnt vmcnt(50)
	v_cndmask_b32_e64 v89, v40, 0, vcc
	s_waitcnt vmcnt(49)
	v_cndmask_b32_e64 v88, v41, 0, vcc
	s_waitcnt vmcnt(48)
	v_cndmask_b32_e64 v68, v42, 0, vcc
	s_waitcnt vmcnt(47)
	v_cndmask_b32_e64 v61, v54, 0, vcc
	s_waitcnt vmcnt(46)
	v_cndmask_b32_e64 v57, v55, 0, vcc
	s_waitcnt vmcnt(45)
	v_cndmask_b32_e64 v58, v56, 0, vcc
	s_waitcnt vmcnt(44)
	v_cndmask_b32_e64 v64, v59, 0, vcc
	s_waitcnt vmcnt(43)
	v_cndmask_b32_e64 v60, v60, 0, vcc
	s_waitcnt vmcnt(42)
	v_cndmask_b32_e64 v56, v63, 0, vcc
	s_waitcnt vmcnt(41)
	v_cndmask_b32_e64 v55, v65, 0, vcc
	s_waitcnt vmcnt(40)
	v_cndmask_b32_e64 v59, v69, 0, vcc
	s_waitcnt vmcnt(39)
	v_cndmask_b32_e64 v54, v70, 0, vcc
	v_cmp_gt_i32_e32 vcc, -3, v7
	v_or_b32_e32 v10, v0, v12
	v_readlane_b32 s43, v252, 50
	s_waitcnt vmcnt(26)
	v_cndmask_b32_e64 v80, v71, 0, vcc
	s_waitcnt vmcnt(25)
	v_cndmask_b32_e64 v78, v72, 0, vcc
	s_waitcnt vmcnt(24)
	v_cndmask_b32_e64 v79, v73, 0, vcc
	v_cmp_gt_i32_e32 vcc, -4, v7
	v_readlane_b32 s44, v252, 51
	v_readlane_b32 s45, v252, 52
	s_waitcnt vmcnt(23)
	v_cndmask_b32_e64 v82, v74, 0, vcc
	s_waitcnt vmcnt(22)
	v_cndmask_b32_e64 v75, v75, 0, vcc
	s_waitcnt vmcnt(21)
	v_cndmask_b32_e64 v81, v76, 0, vcc
	s_waitcnt vmcnt(20)
	v_cndmask_b32_e64 v76, v77, 0, vcc
	s_waitcnt vmcnt(19)
	v_cndmask_b32_e64 v74, v83, 0, vcc
	s_waitcnt vmcnt(18)
	v_cndmask_b32_e64 v77, v84, 0, vcc
	s_waitcnt vmcnt(17)
	v_cndmask_b32_e64 v72, v85, 0, vcc
	s_waitcnt vmcnt(16)
	v_cndmask_b32_e64 v69, v86, 0, vcc
	s_waitcnt vmcnt(15)
	v_cndmask_b32_e64 v73, v87, 0, vcc
	v_readlane_b32 s50, v252, 57
	s_waitcnt vmcnt(14)
	v_cndmask_b32_e64 v70, v90, 0, vcc
	s_waitcnt vmcnt(13)
	v_cndmask_b32_e64 v14, v91, 0, vcc
	s_waitcnt vmcnt(12)
	v_cndmask_b32_e64 v71, v92, 0, vcc
	v_readlane_b32 s51, v252, 58
	v_readlane_b32 s52, v252, 59
	v_readlane_b32 s53, v252, 60
	v_readlane_b32 s54, v252, 61
	v_readlane_b32 s55, v252, 62
	s_barrier
	s_setprio 1
	v_lshlrev_b32_e32 v0, 2, v6
	v_lshl_or_b32 v32, v7, 10, v0
	s_lshl_b32 s6, s6, 7
	v_or_b32_e32 v0, s5, v12
	s_add_u32 s6, s12, s6
	v_add_lshl_u32 v0, v0, v8, 2
	v_ashrrev_i32_e32 v11, 31, v10
	s_addc_u32 s7, s13, 0
	v_add_u32_e32 v39, 0x3000, v0
	v_lshlrev_b32_e32 v40, 4, v31
	v_add_u32_e32 v41, 0x9000, v0
	v_mov_b32_e32 v0, v1
	v_add_u32_e32 v33, 0x1000, v32
	v_add_u32_e32 v34, 0x2000, v32
	v_add_u32_e32 v35, 0x3000, v32
	v_add_u32_e32 v36, 0x4000, v32
	v_add_u32_e32 v37, 0x5000, v32
	v_add_u32_e32 v38, 32, v8
	v_lshl_add_u64 v[6:7], v[10:11], 1, s[6:7]
	v_or_b32_e32 v42, 0x6000, v40
	v_mov_b64_e32 v[10:11], v[0:1]
	v_mov_b64_e32 v[12:13], v[0:1]
